# dilated attention QK: K-fragment LDS prefetch distance deepened from 1 to 2 k-steps ahead (third fragment buffer)
# baseline (speedup 1.0000x reference)
; #define LAS __attribute__((address_space(3)))
; #define MFMA32(a, b, c) __builtin_amdgcn_mfma_f32_32x32x16_bf16((a), (b), (c), 0, 0, 0)
; template <int KSTEPS, class Pol>
; __device__ __forceinline__ void attn_pass(LAS unsigned char* lds, const Pol& P, const bf16_t* qb, int ldq, const bf16_t* kb, int ldk, const bf16_t* vb, int ldv,
;                                           float qs, f32x16 (&O)[4], float& m, float& l) {
;     ...
;         LAS unsigned char* Kb = lds + st * A_STAGE + krow;
;         f32x16 S0, S1;
;         P.fill(S0, S1, qi, half, t, wave);
; #pragma unroll
;         for (int ks = 0; ks < KSTEPS; ++ks) {
;             const int so = ((2 * ks) ^ kx) << 4;
;             const bf16x8 a0 = *(const LAS bf16x8*)(Kb + so);
;             const bf16x8 a1 = *(const LAS bf16x8*)(Kb + 32 * KROWB + so);
;             S0 = MFMA32(a0, qf[ks], S0);
;             S1 = MFMA32(a1, qf[ks], S1);
;         }
;         S0 = S0 * qs; S1 = S1 * qs;
;         float mx = fmaxf(S0[0], S1[0]);
; #pragma unroll
;         for (int i = 1; i < 16; ++i) mx = fmaxf(fmaxf(mx, S0[i]), S1[i]);
;         mx = fmaxf(mx, __shfl_xor(mx, 32));
;         const float mnew = fmaxf(m, mx);
;         const float alpha = __builtin_amdgcn_exp2f(m - mnew);
;         m = mnew;
.LBB0_237:
	s_lshl_b32 s44, s74, 15
	s_add_i32 s44, s44, 0
	v_add_u32_e32 v0, s44, v160
	v_add_u32_e32 v6, v0, v161
	ds_read_b128 v[2:5], v6
	ds_read_b128 v[6:9], v6 offset:8192
	v_add_u32_e32 v200, v0, v162
	ds_read_b128 v[192:195], v200
	ds_read_b128 v[196:199], v200 offset:8192
	v_add_u32_e32 v205, v0, v163
	ds_read_b128 v[226:229], v205
	ds_read_b128 v[10:13], v205 offset:8192
	v_and_b32_e32 v15, 64, v234
	v_xor_b32_e32 v14, 32, v234
	v_add_u32_e32 v15, 64, v15
	s_waitcnt lgkmcnt(5)
	v_mfma_f32_32x32x16_bf16 v[96:111], v[2:5], v[112:115], v[96:111]
	v_cmp_lt_i32_e32 vcc, v14, v15
	s_nop 1
	v_cndmask_b32_e32 v14, v234, v14, vcc
	v_lshlrev_b32_e32 v14, 2, v14
	s_waitcnt lgkmcnt(4)
	v_mfma_f32_32x32x16_bf16 v[80:95], v[6:9], v[112:115], v[80:95]
	v_add_u32_e32 v6, v0, v164
	ds_read_b128 v[2:5], v6
	ds_read_b128 v[6:9], v6 offset:8192
	s_waitcnt lgkmcnt(5)
	v_mfma_f32_32x32x16_bf16 v[96:111], v[192:195], v[116:119], v[96:111]
	s_waitcnt lgkmcnt(4)
	v_mfma_f32_32x32x16_bf16 v[80:95], v[196:199], v[116:119], v[80:95]
	v_add_u32_e32 v200, v0, v165
	ds_read_b128 v[192:195], v200
	ds_read_b128 v[196:199], v200 offset:8192
	s_waitcnt lgkmcnt(5)
	v_mfma_f32_32x32x16_bf16 v[96:111], v[226:229], v[120:123], v[96:111]
	s_waitcnt lgkmcnt(4)
	v_mfma_f32_32x32x16_bf16 v[80:95], v[10:13], v[120:123], v[80:95]
	v_add_u32_e32 v205, v0, v166
	ds_read_b128 v[226:229], v205
	ds_read_b128 v[10:13], v205 offset:8192
	s_waitcnt lgkmcnt(5)
	v_mfma_f32_32x32x16_bf16 v[96:111], v[2:5], v[124:127], v[96:111]
	s_waitcnt lgkmcnt(4)
	v_mfma_f32_32x32x16_bf16 v[80:95], v[6:9], v[124:127], v[80:95]
	v_add_u32_e32 v6, v0, v167
	ds_read_b128 v[2:5], v6
	ds_read_b128 v[6:9], v6 offset:8192
	s_waitcnt lgkmcnt(5)
	v_mfma_f32_32x32x16_bf16 v[96:111], v[192:195], v[128:131], v[96:111]
	s_waitcnt lgkmcnt(4)
	v_mfma_f32_32x32x16_bf16 v[80:95], v[196:199], v[128:131], v[80:95]
	v_add_u32_e32 v200, v0, v168
	ds_read_b128 v[192:195], v200
	ds_read_b128 v[196:199], v200 offset:8192
	s_waitcnt lgkmcnt(5)
	v_mfma_f32_32x32x16_bf16 v[96:111], v[226:229], v[132:135], v[96:111]
	s_waitcnt lgkmcnt(4)
	v_mfma_f32_32x32x16_bf16 v[80:95], v[10:13], v[132:135], v[80:95]
	s_waitcnt lgkmcnt(3)
	v_mfma_f32_32x32x16_bf16 v[96:111], v[2:5], v[136:139], v[96:111]
	s_waitcnt lgkmcnt(2)
	v_mfma_f32_32x32x16_bf16 v[80:95], v[6:9], v[136:139], v[80:95]
	s_waitcnt lgkmcnt(1)
	v_mfma_f32_32x32x16_bf16 v[96:111], v[192:195], v[140:143], v[96:111]
	s_waitcnt lgkmcnt(0)
	v_mfma_f32_32x32x16_bf16 v[80:95], v[196:199], v[140:143], v[80:95]
	v_add_u32_e32 v201, s44, v169
	v_add_u32_e32 v202, s44, v170
	v_add_u32_e32 v203, s44, v171
	v_add_u32_e32 v204, s44, v172
	ds_read_b64_tr_b16 v[192:193], v201 offset:16384
	ds_read_b64_tr_b16 v[194:195], v202 offset:2048
	ds_read_b64_tr_b16 v[196:197], v203 offset:16384
	ds_read_b64_tr_b16 v[198:199], v204 offset:2048
	v_add_u32_e32 v2, s44, v173
	v_add_u32_e32 v3, s44, v174
	v_add_u32_e32 v4, s44, v175
	v_add_u32_e32 v5, s44, v176
	ds_read_b64_tr_b16 v[226:227], v2 offset:16384
	ds_read_b64_tr_b16 v[228:229], v3 offset:2048
	v_max_f32_e32 v15, v96, v80
	v_max3_f32 v15, v15, v97, v81
	v_max3_f32 v15, v15, v98, v82
	v_max3_f32 v15, v15, v99, v83
	v_max3_f32 v15, v15, v100, v84
	v_max3_f32 v15, v15, v101, v85
	v_max3_f32 v15, v15, v102, v86
	v_max3_f32 v15, v15, v103, v87
	v_max3_f32 v15, v15, v104, v88
	v_max3_f32 v15, v15, v105, v89
	v_max3_f32 v15, v15, v106, v90
	v_max3_f32 v15, v15, v107, v91
	v_max3_f32 v15, v15, v108, v92
	v_max3_f32 v15, v15, v109, v93
	v_max3_f32 v15, v15, v110, v94
	v_max3_f32 v15, v15, v111, v95
	v_mul_f32_e64 v15, v15, s20
	ds_bpermute_b32 v14, v14, v15
	s_waitcnt lgkmcnt(0)
	v_max3_f32 v14, v181, v15, v14
	v_sub_f32_e32 v0, v181, v14
	v_exp_f32_e32 v0, v0
	s_nop 0
	v_cmp_neq_f32_e32 vcc, 1.0, v0
	s_cbranch_vccz .LBB0_239
	v_pk_mul_f32 v[78:79], v[78:79], v[0:1] op_sel_hi:[1,0]
	v_pk_mul_f32 v[76:77], v[76:77], v[0:1] op_sel_hi:[1,0]
	v_pk_mul_f32 v[74:75], v[74:75], v[0:1] op_sel_hi:[1,0]
	v_pk_mul_f32 v[72:73], v[72:73], v[0:1] op_sel_hi:[1,0]
	v_pk_mul_f32 v[70:71], v[70:71], v[0:1] op_sel_hi:[1,0]
	v_pk_mul_f32 v[68:69], v[68:69], v[0:1] op_sel_hi:[1,0]
	v_pk_mul_f32 v[66:67], v[66:67], v[0:1] op_sel_hi:[1,0]
	v_pk_mul_f32 v[64:65], v[64:65], v[0:1] op_sel_hi:[1,0]
	v_pk_mul_f32 v[62:63], v[62:63], v[0:1] op_sel_hi:[1,0]
	v_pk_mul_f32 v[60:61], v[60:61], v[0:1] op_sel_hi:[1,0]
	v_pk_mul_f32 v[58:59], v[58:59], v[0:1] op_sel_hi:[1,0]
	v_pk_mul_f32 v[56:57], v[56:57], v[0:1] op_sel_hi:[1,0]
	v_pk_mul_f32 v[54:55], v[54:55], v[0:1] op_sel_hi:[1,0]
	v_pk_mul_f32 v[52:53], v[52:53], v[0:1] op_sel_hi:[1,0]
	v_pk_mul_f32 v[50:51], v[50:51], v[0:1] op_sel_hi:[1,0]
	v_pk_mul_f32 v[48:49], v[48:49], v[0:1] op_sel_hi:[1,0]
	v_pk_mul_f32 v[46:47], v[46:47], v[0:1] op_sel_hi:[1,0]
	v_pk_mul_f32 v[44:45], v[44:45], v[0:1] op_sel_hi:[1,0]
	v_pk_mul_f32 v[42:43], v[42:43], v[0:1] op_sel_hi:[1,0]
	v_pk_mul_f32 v[40:41], v[40:41], v[0:1] op_sel_hi:[1,0]
	v_pk_mul_f32 v[38:39], v[38:39], v[0:1] op_sel_hi:[1,0]
	v_pk_mul_f32 v[36:37], v[36:37], v[0:1] op_sel_hi:[1,0]
	v_pk_mul_f32 v[34:35], v[34:35], v[0:1] op_sel_hi:[1,0]
	v_pk_mul_f32 v[32:33], v[32:33], v[0:1] op_sel_hi:[1,0]
	v_pk_mul_f32 v[30:31], v[30:31], v[0:1] op_sel_hi:[1,0]
	v_pk_mul_f32 v[28:29], v[28:29], v[0:1] op_sel_hi:[1,0]
	v_pk_mul_f32 v[26:27], v[26:27], v[0:1] op_sel_hi:[1,0]
	v_pk_mul_f32 v[24:25], v[24:25], v[0:1] op_sel_hi:[1,0]
	v_pk_mul_f32 v[22:23], v[22:23], v[0:1] op_sel_hi:[1,0]
	v_pk_mul_f32 v[20:21], v[20:21], v[0:1] op_sel_hi:[1,0]
	v_pk_mul_f32 v[18:19], v[18:19], v[0:1] op_sel_hi:[1,0]
	v_pk_mul_f32 v[16:17], v[16:17], v[0:1] op_sel_hi:[1,0]
